# FoX sample loops: two tiles in flight AND double-buffered QK^T fragments (16 loop-invariant VGPRs parked in LDS across the loop)
# baseline (speedup 1.0000x reference)
; template <int MODE, bool SAMPLE>
; __device__ __forceinline__ void attn_unit(const Params& p, char* lds, int b, int h, int qb) {
;     ...
;         WRITET(buf, stg2[NS == 2 ? par : 0]);
;         if (j >= NS) LOADT(j - NS, stg2[NS == 2 ? par : 0]);
.Lfsr_first_f1:
	s_waitcnt vmcnt(0)
	v_lshlrev_b32_e32 v66, 4, v183
	v_add_u32_e32 v66, 0x15000, v66
	ds_write_b128 v66, v[148:151]
	ds_write_b128 v66, v[156:159] offset:8192
	ds_write_b128 v66, v[172:175] offset:16384
	ds_write_b128 v66, v[176:179] offset:24576
	v_mov_b32_e32 v250, v137
	v_mov_b32_e32 v251, v139
	v_mov_b32_e32 v252, v141
	s_lshl_b64 s[4:5], s[54:55], 10
	v_lshl_add_u64 v[66:67], s[4:5], 0, v[168:169]
	v_readlane_b32 s36, v253, 16
	v_lshlrev_b64 v[66:67], 2, v[66:67]
	v_and_b32_e32 v72, 15, v183
	v_lshlrev_b32_e32 v72, 4, v72
	v_sub_u32_e32 v66, v66, v72
	v_readlane_b32 s40, v253, 20
	v_readlane_b32 s41, v253, 21
	v_readlane_b32 s42, v253, 22
	v_readlane_b32 s43, v253, 23
	v_lshl_add_u64 v[68:69], s[40:41], 0, v[66:67]
	v_mov_b32_e32 v165, v1
	v_lshl_add_u64 v[70:71], v[68:69], 0, v[0:1]
	v_lshl_add_u64 v[68:69], v[68:69], 0, v[164:165]
	v_lshl_add_u64 v[66:67], s[42:43], 0, v[66:67]
	global_load_dwordx4 v[234:237], v[70:71], off offset:256 nt
	global_load_dwordx4 v[238:241], v[70:71], off nt
	global_load_dwordx4 v[242:245], v[68:69], off offset:256 nt
	global_load_dwordx4 v[246:249], v[68:69], off nt
	v_lshl_add_u64 v[68:69], v[66:67], 0, v[0:1]
	v_lshl_add_u64 v[66:67], v[66:67], 0, v[164:165]
	global_load_dwordx4 v[210:213], v[68:69], off offset:256 nt
	global_load_dwordx4 v[134:137], v[68:69], off nt
	global_load_dwordx4 v[194:197], v[66:67], off offset:256 nt
	global_load_dwordx4 v[138:141], v[66:67], off nt
	v_cvt_pk_bf16_f32 v66, v102, v103
	v_cvt_pk_bf16_f32 v67, v104, v105
	v_cvt_pk_bf16_f32 v68, v98, v99
	v_cvt_pk_bf16_f32 v69, v100, v101
	ds_write_b128 v133, v[66:69]
	v_cvt_pk_bf16_f32 v66, v110, v111
	v_cvt_pk_bf16_f32 v67, v112, v113
	v_cvt_pk_bf16_f32 v68, v106, v107
	v_cvt_pk_bf16_f32 v69, v108, v109
	ds_write_b128 v198, v[66:69]
	v_cvt_pk_bf16_f32 v66, v122, v123
	v_cvt_pk_bf16_f32 v67, v124, v125
	v_cvt_pk_bf16_f32 v68, v114, v115
	v_cvt_pk_bf16_f32 v69, v116, v117
	s_cmpk_eq_i32 s97, 0xf000
	ds_write_b128 v199, v[66:69] offset:32768
	v_cvt_pk_bf16_f32 v66, v126, v127
	v_cvt_pk_bf16_f32 v67, v128, v129
	v_cvt_pk_bf16_f32 v68, v118, v119
	v_cvt_pk_bf16_f32 v69, v120, v121
	ds_write_b128 v200, v[66:69] offset:32768
	s_branch .Lfsr_join_f1

; __device__ __forceinline__ void qkt(f32x16& p0, f32x16& p1, const char* Ks, const char* Qs, int r32, int hi) {
; #pragma unroll
;     for (int d0 = 0; d0 < 8; ++d0) { const int cb = (d0 * 16 + hi * 8) * 2;
;         const bf16x8 qv = *reinterpret_cast<const bf16x8*>(Qs + KSWZ(r32, cb));
;         const bf16x8 b0 = *reinterpret_cast<const bf16x8*>(Ks + KSWZ(r32, cb));
;         const bf16x8 b1 = *reinterpret_cast<const bf16x8*>(Ks + KSWZ(32 + r32, cb));
;         p0 = __builtin_amdgcn_mfma_f32_32x32x16_bf16(b0, qv, p0, 0, 0, 0);
;         p1 = __builtin_amdgcn_mfma_f32_32x32x16_bf16(b1, qv, p1, 0, 0, 0); }
; }
; template <int MODE, bool SAMPLE>
; __device__ __forceinline__ void attn_unit(const Params& p, char* lds, int b, int h, int qb) {
;     ...
;             const char* Kt = K_lds + buf * 16384; const int vb = vb0 + buf * 16384;
;             f32x16 p0, p1; bf16x8 pa0, pa1, pa2, pa3;
;             if (MODE == 0) {
;                 const float* bt = biasL + j * 64 + 4 * hi;
; #pragma unroll
;                 for (int g = 0; g < 4; ++g) { const f32x4 a = *(const f32x4*)(bt + 8 * g), c = *(const f32x4*)(bt + 32 + 8 * g);
; #pragma unroll
;                     for (int i = 0; i < 4; ++i) { p0[4 * g + i] = a[i]; p1[4 * g + i] = c[i]; } }
;                 qkt(p0, p1, Kt, Qs, r32, hi);
.Lns2_dj_f1:
	s_and_b64 vcc, exec, s[0:1]
	v_readlane_b32 s37, v253, 17
	v_readlane_b32 s38, v253, 18
	v_readlane_b32 s39, v253, 19
	v_readlane_b32 s44, v253, 24
	v_readlane_b32 s45, v253, 25
	v_readlane_b32 s46, v253, 26
	v_readlane_b32 s47, v253, 27
	v_readlane_b32 s48, v253, 28
	v_readlane_b32 s49, v253, 29
	v_readlane_b32 s50, v253, 30
	v_readlane_b32 s51, v253, 31
	s_waitcnt lgkmcnt(0)
	s_barrier
	s_cbranch_vccnz .LBB0_622
	v_add_u32_e32 v78, s97, v214
	v_add_u32_e32 v66, 0x11100, v78
	v_add_u32_e32 v67, 0x11180, v78
	v_add_u32_e32 v70, 0x11120, v78
	v_add_u32_e32 v74, 0x11140, v78
	ds_read_b128 v[82:85], v66
	ds_read_b128 v[66:69], v67
	ds_read_b128 v[86:89], v70
	ds_read_b128 v[90:93], v74
	v_add_u32_e32 v70, 0x111a0, v78
	v_add_u32_e32 v74, 0x111c0, v78
	v_add_u32_e32 v79, 0x11160, v78
	v_add_u32_e32 v78, 0x111e0, v78
	ds_read_b128 v[94:97], v79
	ds_read_b128 v[78:81], v78
	ds_read_b128 v[70:73], v70
	ds_read_b128 v[74:77], v74
	v_add_u32_e32 v165, s33, v182
	ds_read_b128 v[202:205], v165
	ds_read_b128 v[206:209], v182 offset:16384
	ds_read_b128 v[216:219], v182 offset:24576
	v_add_u32_e32 v165, s33, v184
	ds_read_b128 v[148:151], v165
	ds_read_b128 v[156:159], v184 offset:16384
	ds_read_b128 v[172:175], v184 offset:24576
	s_waitcnt lgkmcnt(4)
	v_mfma_f32_32x32x16_bf16 v[82:97], v[206:209], v[202:205], v[82:97]
	s_waitcnt lgkmcnt(3)
	v_mfma_f32_32x32x16_bf16 v[66:81], v[216:219], v[202:205], v[66:81]
	v_add_u32_e32 v165, s33, v185
	ds_read_b128 v[202:205], v165
	ds_read_b128 v[206:209], v185 offset:16384
	ds_read_b128 v[216:219], v185 offset:24576
	s_waitcnt lgkmcnt(4)
	v_mfma_f32_32x32x16_bf16 v[82:97], v[156:159], v[148:151], v[82:97]
	s_waitcnt lgkmcnt(3)
	v_mfma_f32_32x32x16_bf16 v[66:81], v[172:175], v[148:151], v[66:81]
	v_add_u32_e32 v165, s33, v186
	ds_read_b128 v[148:151], v165
	ds_read_b128 v[156:159], v186 offset:16384
	ds_read_b128 v[172:175], v186 offset:24576
	s_waitcnt lgkmcnt(4)
	v_mfma_f32_32x32x16_bf16 v[82:97], v[206:209], v[202:205], v[82:97]
	s_waitcnt lgkmcnt(3)
	v_mfma_f32_32x32x16_bf16 v[66:81], v[216:219], v[202:205], v[66:81]
	v_add_u32_e32 v165, s33, v187
	ds_read_b128 v[202:205], v165
	ds_read_b128 v[206:209], v187 offset:16384
	ds_read_b128 v[216:219], v187 offset:24576
	s_waitcnt lgkmcnt(4)
	v_mfma_f32_32x32x16_bf16 v[82:97], v[156:159], v[148:151], v[82:97]
	s_waitcnt lgkmcnt(3)
	v_mfma_f32_32x32x16_bf16 v[66:81], v[172:175], v[148:151], v[66:81]
	v_add_u32_e32 v165, s33, v188
	ds_read_b128 v[148:151], v165
	ds_read_b128 v[156:159], v188 offset:16384
	ds_read_b128 v[172:175], v188 offset:24576
	s_waitcnt lgkmcnt(4)
	v_mfma_f32_32x32x16_bf16 v[82:97], v[206:209], v[202:205], v[82:97]
	s_waitcnt lgkmcnt(3)
	v_mfma_f32_32x32x16_bf16 v[66:81], v[216:219], v[202:205], v[66:81]
	v_add_u32_e32 v165, s33, v189
	ds_read_b128 v[202:205], v165
	ds_read_b128 v[206:209], v189 offset:16384
	ds_read_b128 v[216:219], v189 offset:24576
	s_waitcnt lgkmcnt(4)
	v_mfma_f32_32x32x16_bf16 v[82:97], v[156:159], v[148:151], v[82:97]
	s_waitcnt lgkmcnt(3)
	v_mfma_f32_32x32x16_bf16 v[66:81], v[172:175], v[148:151], v[66:81]
	v_add_u32_e32 v165, s33, v190
	ds_read_b128 v[148:151], v165
	ds_read_b128 v[156:159], v190 offset:16384
	ds_read_b128 v[172:175], v190 offset:24576
	s_waitcnt lgkmcnt(4)
	v_mfma_f32_32x32x16_bf16 v[82:97], v[206:209], v[202:205], v[82:97]
	s_waitcnt lgkmcnt(3)
	v_mfma_f32_32x32x16_bf16 v[66:81], v[216:219], v[202:205], v[66:81]
	s_waitcnt lgkmcnt(1)
	v_mfma_f32_32x32x16_bf16 v[82:97], v[156:159], v[148:151], v[82:97]
	s_waitcnt lgkmcnt(0)
; __device__ __forceinline__ int crow(int r, int hi) { return (r & 3) + 8 * (r >> 2) + 4 * hi; }
; template <int MODE, bool SAMPLE>
; __device__ __forceinline__ void attn_unit(const Params& p, char* lds, int b, int h, int qb) {
;     ...
;                 float pmax = p0[0];
; #pragma unroll
;                 for (int r = 1; r < 16; ++r) pmax = fmaxf(pmax, p0[r]);
; #pragma unroll
;                 for (int r = 0; r < 16; ++r) pmax = fmaxf(pmax, p1[r]);
;                 { auto rr = __builtin_amdgcn_permlane32_swap(__float_as_uint(pmax), __float_as_uint(pmax), false, false); pmax = fmaxf(__uint_as_float(rr[0]), __uint_as_float(rr[1])); }
;                 float alpha = 1.f;
;                 if (!__all(pmax - m_reg <= 8.f)) { const float mn = fmaxf(m_reg, pmax); alpha = __builtin_amdgcn_exp2f(m_reg - mn); m_reg = mn; }
;                 float ps = 0.f;
; #pragma unroll
;                 for (int r = 0; r < 16; ++r) { p0[r] = __builtin_amdgcn_exp2f(p0[r] - m_reg); p1[r] = __builtin_amdgcn_exp2f(p1[r] - m_reg); ps += p0[r] + p1[r]; }
;                 { auto rr = __builtin_amdgcn_permlane32_swap(__float_as_uint(ps), __float_as_uint(ps), false, false); ps = __uint_as_float(rr[0]) + __uint_as_float(rr[1]); }
;                 l_reg = l_reg * alpha + ps;
;                 if (__any(alpha < 1.f)) { if (hi == 0) wsc[r32] = alpha; asm volatile("s_waitcnt lgkmcnt(0)" ::: "memory");
; #pragma unroll
;                     for (int d = 0; d < 4; ++d)
; #pragma unroll
;                         for (int r = 0; r < 16; ++r) o[d][r] *= wsc[crow(r, hi)]; }
	v_mfma_f32_32x32x16_bf16 v[66:81], v[172:175], v[148:151], v[66:81]
	s_nop 1
	s_nop 9
	v_max_f32_e32 v165, v83, v83
	v_max_f32_e32 v202, v82, v82
	v_max_f32_e32 v165, v202, v165
	v_max3_f32 v165, v165, v84, v85
	v_max3_f32 v165, v165, v86, v87
	v_max3_f32 v165, v165, v88, v89
	v_max3_f32 v165, v165, v90, v91
	v_max3_f32 v165, v165, v92, v93
	v_max3_f32 v165, v165, v94, v95
	v_max3_f32 v165, v165, v96, v97
	v_max3_f32 v165, v165, v66, v67
	v_max3_f32 v165, v165, v68, v69
	v_max3_f32 v165, v165, v70, v71
	v_max3_f32 v165, v165, v72, v73
	v_max3_f32 v165, v165, v74, v75
	v_max3_f32 v165, v165, v76, v77
	v_max3_f32 v165, v165, v78, v79
	v_max3_f32 v165, v165, v80, v81
	v_mov_b32_e32 v202, v165
	s_nop 1
	v_permlane32_swap_b32_e32 v165, v202
	v_max_f32_e32 v202, v202, v202
	v_max_f32_e32 v165, v165, v165
	v_max_f32_e32 v165, v165, v202
	v_sub_f32_e32 v202, v165, v163
	v_cmp_ge_f32_e32 vcc, s83, v202
	s_cmp_eq_u64 vcc, exec
	v_max_f32_e32 v202, v163, v163
	s_cselect_b64 vcc, -1, 0
	v_max_f32_e32 v165, v202, v165
	v_sub_f32_e32 v202, v163, v165
	v_cndmask_b32_e32 v163, v165, v163, vcc
	v_sub_f32_e32 v82, v82, v163
	v_sub_f32_e32 v66, v66, v163
	v_exp_f32_e32 v165, v82
	v_exp_f32_e32 v82, v66
	v_exp_f32_e32 v203, v202
	v_sub_f32_e32 v67, v67, v163
	v_sub_f32_e32 v68, v68, v163
	v_add_f32_e32 v66, v165, v82
	v_add_f32_e32 v202, 0, v66
	v_sub_f32_e32 v66, v83, v163
	v_exp_f32_e32 v66, v66
	v_exp_f32_e32 v83, v67
	v_sub_f32_e32 v69, v69, v163
	v_sub_f32_e32 v70, v70, v163
	v_exp_f32_e32 v70, v70
	v_add_f32_e32 v67, v66, v83
	v_add_f32_e32 v202, v67, v202
	v_sub_f32_e32 v67, v84, v163
	v_exp_f32_e32 v67, v67
	v_exp_f32_e32 v84, v68
	v_sub_f32_e32 v71, v71, v163
	v_exp_f32_e32 v71, v71
	v_sub_f32_e32 v72, v72, v163
	v_add_f32_e32 v68, v67, v84
	v_add_f32_e32 v202, v68, v202
	v_sub_f32_e32 v68, v85, v163
	v_exp_f32_e32 v68, v68
	v_exp_f32_e32 v85, v69
	v_exp_f32_e32 v72, v72
	v_sub_f32_e32 v73, v73, v163
	v_exp_f32_e32 v73, v73
	v_add_f32_e32 v69, v68, v85
	v_add_f32_e32 v202, v69, v202
	v_sub_f32_e32 v69, v86, v163
	v_exp_f32_e32 v69, v69
	v_sub_f32_e32 v74, v74, v163
	v_exp_f32_e32 v74, v74
	v_sub_f32_e32 v75, v75, v163
	v_add_f32_e32 v86, v69, v70
	v_add_f32_e32 v202, v86, v202
	v_sub_f32_e32 v86, v87, v163
	v_exp_f32_e32 v86, v86
	v_exp_f32_e32 v75, v75
	v_sub_f32_e32 v76, v76, v163
	v_exp_f32_e32 v76, v76
	v_add_f32_e32 v87, v86, v71
	v_add_f32_e32 v202, v87, v202
	v_sub_f32_e32 v87, v88, v163
	v_exp_f32_e32 v87, v87
	v_sub_f32_e32 v77, v77, v163
	v_exp_f32_e32 v77, v77
	v_sub_f32_e32 v78, v78, v163
	v_add_f32_e32 v88, v87, v72
	v_add_f32_e32 v202, v88, v202
	v_sub_f32_e32 v88, v89, v163
	v_exp_f32_e32 v88, v88
	v_exp_f32_e32 v78, v78
	v_sub_f32_e32 v79, v79, v163
	v_exp_f32_e32 v79, v79
	v_add_f32_e32 v89, v88, v73
	v_add_f32_e32 v202, v89, v202
	v_sub_f32_e32 v89, v90, v163
	v_exp_f32_e32 v89, v89
	v_sub_f32_e32 v80, v80, v163
	v_exp_f32_e32 v80, v80
	v_sub_f32_e32 v81, v81, v163
	v_add_f32_e32 v90, v89, v74
	v_add_f32_e32 v202, v90, v202
	v_sub_f32_e32 v90, v91, v163
	v_exp_f32_e32 v90, v90
	v_exp_f32_e32 v81, v81
	v_add_f32_e32 v91, v90, v75
	v_add_f32_e32 v202, v91, v202
	v_sub_f32_e32 v91, v92, v163
	v_exp_f32_e32 v91, v91
	s_nop 0
	v_add_f32_e32 v92, v91, v76
	v_add_f32_e32 v202, v92, v202
	v_sub_f32_e32 v92, v93, v163
	v_exp_f32_e32 v92, v92
	s_nop 0
	v_add_f32_e32 v93, v92, v77
	v_add_f32_e32 v202, v93, v202
	v_sub_f32_e32 v93, v94, v163
	v_exp_f32_e32 v93, v93
	s_nop 0
	v_add_f32_e32 v94, v93, v78
	v_add_f32_e32 v202, v94, v202
	v_sub_f32_e32 v94, v95, v163
	v_exp_f32_e32 v94, v94
	s_nop 0
	v_add_f32_e32 v95, v94, v79
	v_add_f32_e32 v202, v95, v202
	v_sub_f32_e32 v95, v96, v163
	v_exp_f32_e32 v95, v95
	s_nop 0
	v_add_f32_e32 v96, v95, v80
	v_add_f32_e32 v202, v96, v202
	v_sub_f32_e32 v96, v97, v163
	v_exp_f32_e32 v96, v96
	s_nop 0
	v_add_f32_e32 v97, v96, v81
	v_add_f32_e32 v202, v97, v202
	v_cndmask_b32_e64 v97, v203, 1.0, vcc
	v_mov_b32_e32 v203, v202
	s_nop 1
	v_permlane32_swap_b32_e32 v202, v203
	v_cmp_gt_f32_e32 vcc, 1.0, v97
	s_cbranch_vccz .LBB0_621
	s_and_saveexec_b64 s[4:5], s[14:15]
	ds_write_b32 v145, v97
	s_or_b64 exec, exec, s[4:5]
	s_waitcnt lgkmcnt(0)
	ds_read_b128 v[204:207], v147 offset:96
	ds_read_b128 v[216:219], v147 offset:64
	ds_read_b128 v[220:223], v147 offset:32
	ds_read_b128 v[224:227], v147
	s_waitcnt lgkmcnt(3)
	v_pk_mul_f32 v[64:65], v[64:65], v[206:207]
	s_waitcnt lgkmcnt(2)
	v_pk_mul_f32 v[60:61], v[60:61], v[218:219]
	s_waitcnt lgkmcnt(1)
	v_pk_mul_f32 v[56:57], v[56:57], v[222:223]
	s_waitcnt lgkmcnt(0)
	v_pk_mul_f32 v[52:53], v[52:53], v[226:227]
	v_pk_mul_f32 v[62:63], v[62:63], v[204:205]
	v_pk_mul_f32 v[58:59], v[58:59], v[216:217]
	v_pk_mul_f32 v[54:55], v[54:55], v[220:221]
	v_pk_mul_f32 v[50:51], v[50:51], v[224:225]
	v_pk_mul_f32 v[48:49], v[48:49], v[206:207]
	v_pk_mul_f32 v[44:45], v[44:45], v[218:219]
	v_pk_mul_f32 v[40:41], v[40:41], v[222:223]
	v_pk_mul_f32 v[36:37], v[36:37], v[226:227]
	v_pk_mul_f32 v[46:47], v[46:47], v[204:205]
	v_pk_mul_f32 v[42:43], v[42:43], v[216:217]
	v_pk_mul_f32 v[38:39], v[38:39], v[220:221]
	v_pk_mul_f32 v[34:35], v[34:35], v[224:225]
	v_pk_mul_f32 v[32:33], v[32:33], v[206:207]
	v_pk_mul_f32 v[28:29], v[28:29], v[218:219]
	v_pk_mul_f32 v[24:25], v[24:25], v[222:223]
	v_pk_mul_f32 v[20:21], v[20:21], v[226:227]
	v_pk_mul_f32 v[30:31], v[30:31], v[204:205]
	v_pk_mul_f32 v[26:27], v[26:27], v[216:217]
	v_pk_mul_f32 v[22:23], v[22:23], v[220:221]
	v_pk_mul_f32 v[18:19], v[18:19], v[224:225]
	v_pk_mul_f32 v[16:17], v[16:17], v[206:207]
	v_pk_mul_f32 v[12:13], v[12:13], v[218:219]
	v_pk_mul_f32 v[8:9], v[8:9], v[222:223]
	v_pk_mul_f32 v[4:5], v[4:5], v[226:227]
	v_pk_mul_f32 v[14:15], v[14:15], v[204:205]
	v_pk_mul_f32 v[10:11], v[10:11], v[216:217]
	v_pk_mul_f32 v[6:7], v[6:7], v[220:221]
	v_pk_mul_f32 v[2:3], v[2:3], v[224:225]

; __device__ __forceinline__ int crow(int r, int hi) { return (r & 3) + 8 * (r >> 2) + 4 * hi; }
; __device__ __forceinline__ void qkt(f32x16& p0, f32x16& p1, const char* Ks, const char* Qs, int r32, int hi) {
; #pragma unroll
;     for (int d0 = 0; d0 < 8; ++d0) { const int cb = (d0 * 16 + hi * 8) * 2;
;         const bf16x8 qv = *reinterpret_cast<const bf16x8*>(Qs + KSWZ(r32, cb));
;         const bf16x8 b0 = *reinterpret_cast<const bf16x8*>(Ks + KSWZ(r32, cb));
;         const bf16x8 b1 = *reinterpret_cast<const bf16x8*>(Ks + KSWZ(32 + r32, cb));
;         p0 = __builtin_amdgcn_mfma_f32_32x32x16_bf16(b0, qv, p0, 0, 0, 0);
;         p1 = __builtin_amdgcn_mfma_f32_32x32x16_bf16(b1, qv, p1, 0, 0, 0); }
; }
; template <int MODE, bool SAMPLE>
; __device__ __forceinline__ void attn_unit(const Params& p, char* lds, int b, int h, int qb) {
;     ...
;                 const float* bt = biasL + j * 64 + 4 * hi;
; #pragma unroll
;                 for (int g = 0; g < 4; ++g) { const f32x4 a = *(const f32x4*)(bt + 8 * g), c = *(const f32x4*)(bt + 32 + 8 * g);
; #pragma unroll
;                     for (int i = 0; i < 4; ++i) { p0[4 * g + i] = a[i]; p1[4 * g + i] = c[i]; } }
;                 qkt(p0, p1, Kt, Qs, r32, hi);
;                 if (j == jd) {
; #pragma unroll
;                     for (int r = 0; r < 16; ++r) { const int kp = j * 64 + crow(r, hi); if (kp > qpos) p0[r] = -1e30f; if (kp + 32 > qpos) p1[r] = -1e30f; } }
.LBB0_624:
	s_and_b64 vcc, exec, s[0:1]
	v_add_u32_e32 v202, 0, v182
	v_add_u32_e32 v203, 0, v184
	v_add_u32_e32 v204, 0, v185
	v_add_u32_e32 v205, 0, v186
	v_add_u32_e32 v206, 0, v187
	v_add_u32_e32 v207, 0, v188
	v_add_u32_e32 v208, 0, v189
	v_add_u32_e32 v209, 0, v190
	s_waitcnt lgkmcnt(0)
	s_barrier
	s_cbranch_vccnz .LBB0_614
	v_add_u32_e32 v94, s97, v214
	v_add_u32_e32 v66, 0x11000, v94
	v_add_u32_e32 v70, 0x11080, v94
	ds_read_b128 v[66:69], v66
	ds_read_b128 v[82:85], v70
	v_add_u32_e32 v70, 0x11020, v94
	v_add_u32_e32 v74, 0x11040, v94
	v_add_u32_e32 v78, 0x11060, v94
	ds_read_b128 v[70:73], v70
	ds_read_b128 v[74:77], v74
	ds_read_b128 v[78:81], v78
	v_add_u32_e32 v86, 0x110a0, v94
	v_add_u32_e32 v95, 0x110c0, v94
	v_add_u32_e32 v94, 0x110e0, v94
	ds_read_b128 v[86:89], v86
	ds_read_b128 v[90:93], v95
	ds_read_b128 v[94:97], v94
	s_cmp_lg_u32 s97, 0
	v_add_u32_e32 v165, s33, v182
	ds_read_b128 v[220:223], v165
	ds_read_b128 v[216:219], v202
	ds_read_b128 v[176:179], v202 offset:8192
	v_add_u32_e32 v165, s33, v184
	ds_read_b128 v[148:151], v165
	ds_read_b128 v[156:159], v203
	ds_read_b128 v[172:175], v203 offset:8192
	s_waitcnt lgkmcnt(4)
	v_mfma_f32_32x32x16_bf16 v[66:81], v[216:219], v[220:223], v[66:81]
	s_waitcnt lgkmcnt(3)
	v_mfma_f32_32x32x16_bf16 v[82:97], v[176:179], v[220:223], v[82:97]
	v_add_u32_e32 v165, s33, v185
	ds_read_b128 v[220:223], v165
	ds_read_b128 v[216:219], v204
	ds_read_b128 v[176:179], v204 offset:8192
	s_waitcnt lgkmcnt(4)
	v_mfma_f32_32x32x16_bf16 v[66:81], v[156:159], v[148:151], v[66:81]
	s_waitcnt lgkmcnt(3)
	v_mfma_f32_32x32x16_bf16 v[82:97], v[172:175], v[148:151], v[82:97]
	v_add_u32_e32 v165, s33, v186
	ds_read_b128 v[148:151], v165
	ds_read_b128 v[156:159], v205
	ds_read_b128 v[172:175], v205 offset:8192
	s_waitcnt lgkmcnt(4)
	v_mfma_f32_32x32x16_bf16 v[66:81], v[216:219], v[220:223], v[66:81]
	s_waitcnt lgkmcnt(3)
	v_mfma_f32_32x32x16_bf16 v[82:97], v[176:179], v[220:223], v[82:97]
	v_add_u32_e32 v165, s33, v187
	ds_read_b128 v[220:223], v165
	ds_read_b128 v[216:219], v206
	ds_read_b128 v[176:179], v206 offset:8192
	s_waitcnt lgkmcnt(4)
	v_mfma_f32_32x32x16_bf16 v[66:81], v[156:159], v[148:151], v[66:81]
	s_waitcnt lgkmcnt(3)
	v_mfma_f32_32x32x16_bf16 v[82:97], v[172:175], v[148:151], v[82:97]
	v_add_u32_e32 v165, s33, v188
	ds_read_b128 v[148:151], v165
	ds_read_b128 v[156:159], v207
	ds_read_b128 v[172:175], v207 offset:8192
	s_waitcnt lgkmcnt(4)
	v_mfma_f32_32x32x16_bf16 v[66:81], v[216:219], v[220:223], v[66:81]
	s_waitcnt lgkmcnt(3)
	v_mfma_f32_32x32x16_bf16 v[82:97], v[176:179], v[220:223], v[82:97]
	v_add_u32_e32 v165, s33, v189
	ds_read_b128 v[220:223], v165
	ds_read_b128 v[216:219], v208
	ds_read_b128 v[176:179], v208 offset:8192
	s_waitcnt lgkmcnt(4)
	v_mfma_f32_32x32x16_bf16 v[66:81], v[156:159], v[148:151], v[66:81]
	s_waitcnt lgkmcnt(3)
	v_mfma_f32_32x32x16_bf16 v[82:97], v[172:175], v[148:151], v[82:97]
	v_add_u32_e32 v165, s33, v190
	ds_read_b128 v[148:151], v165
	ds_read_b128 v[156:159], v209
	ds_read_b128 v[172:175], v209 offset:8192
	s_waitcnt lgkmcnt(4)
	v_mfma_f32_32x32x16_bf16 v[66:81], v[216:219], v[220:223], v[66:81]
	s_waitcnt lgkmcnt(3)
	v_mfma_f32_32x32x16_bf16 v[82:97], v[176:179], v[220:223], v[82:97]
	s_waitcnt lgkmcnt(1)
	v_mfma_f32_32x32x16_bf16 v[66:81], v[156:159], v[148:151], v[66:81]
	s_waitcnt lgkmcnt(0)
	v_mfma_f32_32x32x16_bf16 v[82:97], v[172:175], v[148:151], v[82:97]
	s_nop 1
	s_cbranch_scc1 .LBB0_627
	s_nop 10
	v_mov_b32_e32 v82, 0xf149f2ca
	v_cndmask_b32_e64 v74, v66, v82, s[22:23]
	v_cndmask_b32_e64 v66, v74, v66, s[24:25]
	v_cndmask_b32_e64 v67, v82, v67, s[24:25]
	v_cndmask_b32_e64 v68, v68, v82, s[26:27]
	v_cndmask_b32_e64 v69, v69, v82, s[28:29]
	v_cndmask_b32_e64 v70, v70, v82, s[30:31]
	v_cndmask_b32_e64 v71, v71, v82, s[34:35]
	v_cndmask_b32_e64 v72, v72, v82, s[16:17]
	v_cndmask_b32_e64 v73, v73, v82, s[88:89]
	v_mov_b32_e32 v83, v82
	v_mov_b32_e32 v84, v82
	v_mov_b32_e32 v85, v82
	v_mov_b32_e32 v86, v82
	v_mov_b32_e32 v87, v82
	v_mov_b32_e32 v88, v82
	v_mov_b32_e32 v89, v82
	v_mov_b32_e32 v90, v82
	v_mov_b32_e32 v91, v82
	v_mov_b32_e32 v92, v82
	v_mov_b32_e32 v93, v82
	v_mov_b32_e32 v94, v82
	v_mov_b32_e32 v95, v82
	v_mov_b32_e32 v96, v82
	v_mov_b32_e32 v97, v82
	v_mov_b32_e32 v74, v82
	v_mov_b32_e32 v75, v82
	v_mov_b32_e32 v76, v82
	v_mov_b32_e32 v77, v82
	v_mov_b32_e32 v78, v82
	v_mov_b32_e32 v79, v82
	v_mov_b32_e32 v80, v82
	v_mov_b32_e32 v81, v82

; template <int MODE, bool SAMPLE>
; __device__ __forceinline__ void attn_unit(const Params& p, char* lds, int b, int h, int qb) {
;     ...
;     if (wact && var < 1) {
;         bf16_t* MIX = (bf16_t*)(p.ws + (var == 0 ? WS_MIX : WS_ACT));
;         const size_t rbase = SAMPLE ? (size_t)(MP + b * TS) : (size_t)(b * SEQ + qb * 256 + wid * 32);
;         constexpr int NIT = SAMPLE ? 4 : 8; const int er = lane >> 4, ec = (lane & 15) * 8;
.LBB0_630:
	s_waitcnt vmcnt(0)
	v_mov_b32_e32 v137, v250
	v_mov_b32_e32 v139, v251
	v_mov_b32_e32 v141, v252
	v_lshlrev_b32_e32 v250, 4, v183
	v_add_u32_e32 v250, 0x15000, v250
	ds_read_b128 v[148:151], v250
	ds_read_b128 v[156:159], v250 offset:8192
	ds_read_b128 v[172:175], v250 offset:16384
	ds_read_b128 v[176:179], v250 offset:24576
	s_waitcnt lgkmcnt(0)
	v_lshlrev_b32_e32 v134, 5, v183
	v_lshlrev_b32_e32 v135, 8, v131
	v_or_b32_e32 v136, 4, v130
	v_or_b32_e32 v138, 8, v130
	v_or_b32_e32 v140, 12, v130
	v_lshlrev_b32_e32 v194, 8, v130
	v_lshlrev_b32_e32 v195, 8, v136
	v_lshlrev_b32_e32 v196, 8, v138
	v_lshlrev_b32_e32 v197, 8, v140
	v_and_b32_e32 v210, 15, v183
	v_lshlrev_b32_e32 v211, 4, v183
	v_lshrrev_b32_e32 v212, 4, v183
	v_add_u32_e32 v213, 32, v212
	s_andn2_b64 vcc, exec, s[72:73]
	s_mov_b64 s[0:1], -1
	s_cbranch_vccnz .LBB0_632
	s_mov_b32 s3, s55
	s_mov_b64 s[0:1], 0

; template <int MODE, bool SAMPLE>
; __device__ __forceinline__ void attn_unit(const Params& p, char* lds, int b, int h, int qb) {
;     ...
;         WRITET(buf, stg2[NS == 2 ? par : 0]);
;         if (j >= NS) LOADT(j - NS, stg2[NS == 2 ? par : 0]);
.Lfsr_first_f2:
	s_waitcnt vmcnt(0)
	v_lshlrev_b32_e32 v66, 4, v183
	v_add_u32_e32 v66, 0x15000, v66
	ds_write_b128 v66, v[136:139]
	ds_write_b128 v66, v[154:157] offset:8192
	ds_write_b128 v66, v[170:173] offset:16384
	ds_write_b128 v66, v[174:177] offset:24576
	v_mov_b32_e32 v250, v141
	v_mov_b32_e32 v251, v143
	v_mov_b32_e32 v252, v130
	s_lshl_b64 s[2:3], s[52:53], 10
	v_lshl_add_u64 v[66:67], s[2:3], 0, v[166:167]
	v_readlane_b32 s36, v253, 16
	v_lshlrev_b64 v[66:67], 2, v[66:67]
	v_and_b32_e32 v72, 15, v183
	v_lshlrev_b32_e32 v72, 4, v72
	v_sub_u32_e32 v66, v66, v72
	v_readlane_b32 s40, v253, 20
	v_readlane_b32 s41, v253, 21
	v_readlane_b32 s42, v253, 22
	v_readlane_b32 s43, v253, 23
	v_lshl_add_u64 v[68:69], s[40:41], 0, v[66:67]
	v_mov_b32_e32 v163, v1
	v_lshl_add_u64 v[70:71], v[68:69], 0, v[0:1]
	v_lshl_add_u64 v[68:69], v[68:69], 0, v[162:163]
	v_lshl_add_u64 v[66:67], s[42:43], 0, v[66:67]
	global_load_dwordx4 v[230:233], v[70:71], off offset:256 nt
	global_load_dwordx4 v[234:237], v[70:71], off nt
	global_load_dwordx4 v[238:241], v[68:69], off offset:256 nt
	global_load_dwordx4 v[242:245], v[68:69], off nt
	v_lshl_add_u64 v[68:69], v[66:67], 0, v[0:1]
	v_lshl_add_u64 v[66:67], v[66:67], 0, v[162:163]
	global_load_dwordx4 v[246:249], v[68:69], off offset:256 nt
	global_load_dwordx4 v[130:133], v[68:69], off nt
	global_load_dwordx4 v[192:195], v[66:67], off offset:256 nt
	global_load_dwordx4 v[140:143], v[66:67], off nt
	v_cvt_pk_bf16_f32 v66, v102, v103
	v_cvt_pk_bf16_f32 v67, v104, v105
	v_cvt_pk_bf16_f32 v68, v98, v99
	v_cvt_pk_bf16_f32 v69, v100, v101
	ds_write_b128 v198, v[66:69]
	v_cvt_pk_bf16_f32 v66, v110, v111
	v_cvt_pk_bf16_f32 v67, v112, v113
	v_cvt_pk_bf16_f32 v68, v106, v107
	v_cvt_pk_bf16_f32 v69, v108, v109
	ds_write_b128 v199, v[66:69]
	v_cvt_pk_bf16_f32 v66, v122, v123
	v_cvt_pk_bf16_f32 v67, v124, v125
	v_cvt_pk_bf16_f32 v68, v114, v115
	v_cvt_pk_bf16_f32 v69, v116, v117
	s_cmpk_eq_i32 s96, 0xf000
	ds_write_b128 v200, v[66:69] offset:32768
	v_cvt_pk_bf16_f32 v66, v126, v127
	v_cvt_pk_bf16_f32 v67, v128, v129
	v_cvt_pk_bf16_f32 v68, v118, v119
	v_cvt_pk_bf16_f32 v69, v120, v121
	ds_write_b128 v201, v[66:69] offset:32768
	s_branch .Lfsr_join_f2

; __device__ __forceinline__ void qkt(f32x16& p0, f32x16& p1, const char* Ks, const char* Qs, int r32, int hi) {
; #pragma unroll
;     for (int d0 = 0; d0 < 8; ++d0) { const int cb = (d0 * 16 + hi * 8) * 2;
;         const bf16x8 qv = *reinterpret_cast<const bf16x8*>(Qs + KSWZ(r32, cb));
;         const bf16x8 b0 = *reinterpret_cast<const bf16x8*>(Ks + KSWZ(r32, cb));
;         const bf16x8 b1 = *reinterpret_cast<const bf16x8*>(Ks + KSWZ(32 + r32, cb));
;         p0 = __builtin_amdgcn_mfma_f32_32x32x16_bf16(b0, qv, p0, 0, 0, 0);
;         p1 = __builtin_amdgcn_mfma_f32_32x32x16_bf16(b1, qv, p1, 0, 0, 0); }
; }
; template <int MODE, bool SAMPLE>
; __device__ __forceinline__ void attn_unit(const Params& p, char* lds, int b, int h, int qb) {
;     ...
;             const char* Kt = K_lds + buf * 16384; const int vb = vb0 + buf * 16384;
;             f32x16 p0, p1; bf16x8 pa0, pa1, pa2, pa3;
;             if (MODE == 0) {
;                 const float* bt = biasL + j * 64 + 4 * hi;
; #pragma unroll
;                 for (int g = 0; g < 4; ++g) { const f32x4 a = *(const f32x4*)(bt + 8 * g), c = *(const f32x4*)(bt + 32 + 8 * g);
; #pragma unroll
;                     for (int i = 0; i < 4; ++i) { p0[4 * g + i] = a[i]; p1[4 * g + i] = c[i]; } }
;                 qkt(p0, p1, Kt, Qs, r32, hi);
.Lns2_dj_f2:
	s_and_b64 vcc, exec, s[0:1]
	v_readlane_b32 s37, v253, 17
	v_readlane_b32 s38, v253, 18
	v_readlane_b32 s39, v253, 19
	v_readlane_b32 s44, v253, 24
	v_readlane_b32 s45, v253, 25
	v_readlane_b32 s46, v253, 26
	v_readlane_b32 s47, v253, 27
	v_readlane_b32 s48, v253, 28
	v_readlane_b32 s49, v253, 29
	v_readlane_b32 s50, v253, 30
	v_readlane_b32 s51, v253, 31
	s_waitcnt lgkmcnt(0)
	s_barrier
	s_cbranch_vccnz .LBB0_851
	v_add_u32_e32 v78, s96, v135
	v_add_u32_e32 v66, 0x11100, v78
	v_add_u32_e32 v67, 0x11180, v78
	v_add_u32_e32 v70, 0x11120, v78
	v_add_u32_e32 v74, 0x11140, v78
	ds_read_b128 v[82:85], v66
	ds_read_b128 v[66:69], v67
	ds_read_b128 v[86:89], v70
	ds_read_b128 v[90:93], v74
	v_add_u32_e32 v70, 0x111a0, v78
	v_add_u32_e32 v74, 0x111c0, v78
	v_add_u32_e32 v79, 0x11160, v78
	v_add_u32_e32 v78, 0x111e0, v78
	ds_read_b128 v[94:97], v79
	ds_read_b128 v[78:81], v78
	ds_read_b128 v[70:73], v70
	ds_read_b128 v[74:77], v74
	v_add_u32_e32 v163, s33, v181
	ds_read_b128 v[204:207], v163
	ds_read_b128 v[212:215], v181 offset:16384
	ds_read_b128 v[216:219], v181 offset:24576
	v_add_u32_e32 v163, s33, v182
	ds_read_b128 v[136:139], v163
	ds_read_b128 v[154:157], v182 offset:16384
	ds_read_b128 v[170:173], v182 offset:24576
	s_waitcnt lgkmcnt(4)
	v_mfma_f32_32x32x16_bf16 v[82:97], v[212:215], v[204:207], v[82:97]
	s_waitcnt lgkmcnt(3)
	v_mfma_f32_32x32x16_bf16 v[66:81], v[216:219], v[204:207], v[66:81]
	v_add_u32_e32 v163, s33, v184
	ds_read_b128 v[204:207], v163
	ds_read_b128 v[212:215], v184 offset:16384
	ds_read_b128 v[216:219], v184 offset:24576
	s_waitcnt lgkmcnt(4)
	v_mfma_f32_32x32x16_bf16 v[82:97], v[154:157], v[136:139], v[82:97]
	s_waitcnt lgkmcnt(3)
	v_mfma_f32_32x32x16_bf16 v[66:81], v[170:173], v[136:139], v[66:81]
	v_add_u32_e32 v163, s33, v185
	ds_read_b128 v[136:139], v163
	ds_read_b128 v[154:157], v185 offset:16384
	ds_read_b128 v[170:173], v185 offset:24576
	s_waitcnt lgkmcnt(4)
	v_mfma_f32_32x32x16_bf16 v[82:97], v[212:215], v[204:207], v[82:97]
	s_waitcnt lgkmcnt(3)
	v_mfma_f32_32x32x16_bf16 v[66:81], v[216:219], v[204:207], v[66:81]
	v_add_u32_e32 v163, s33, v186
	ds_read_b128 v[204:207], v163
	ds_read_b128 v[212:215], v186 offset:16384
	ds_read_b128 v[216:219], v186 offset:24576
	s_waitcnt lgkmcnt(4)
	v_mfma_f32_32x32x16_bf16 v[82:97], v[154:157], v[136:139], v[82:97]
	s_waitcnt lgkmcnt(3)
	v_mfma_f32_32x32x16_bf16 v[66:81], v[170:173], v[136:139], v[66:81]
	v_add_u32_e32 v163, s33, v187
	ds_read_b128 v[136:139], v163
	ds_read_b128 v[154:157], v187 offset:16384
	ds_read_b128 v[170:173], v187 offset:24576
	s_waitcnt lgkmcnt(4)
	v_mfma_f32_32x32x16_bf16 v[82:97], v[212:215], v[204:207], v[82:97]
	s_waitcnt lgkmcnt(3)
	v_mfma_f32_32x32x16_bf16 v[66:81], v[216:219], v[204:207], v[66:81]
	v_add_u32_e32 v163, s33, v188
	ds_read_b128 v[204:207], v163
	ds_read_b128 v[212:215], v188 offset:16384
	ds_read_b128 v[216:219], v188 offset:24576
	s_waitcnt lgkmcnt(4)
	v_mfma_f32_32x32x16_bf16 v[82:97], v[154:157], v[136:139], v[82:97]
	s_waitcnt lgkmcnt(3)
	v_mfma_f32_32x32x16_bf16 v[66:81], v[170:173], v[136:139], v[66:81]
	v_add_u32_e32 v163, s33, v189
	ds_read_b128 v[136:139], v163
	ds_read_b128 v[154:157], v189 offset:16384
	ds_read_b128 v[170:173], v189 offset:24576
	s_waitcnt lgkmcnt(4)
	v_mfma_f32_32x32x16_bf16 v[82:97], v[212:215], v[204:207], v[82:97]
	s_waitcnt lgkmcnt(3)
	v_mfma_f32_32x32x16_bf16 v[66:81], v[216:219], v[204:207], v[66:81]
	s_waitcnt lgkmcnt(1)
	v_mfma_f32_32x32x16_bf16 v[82:97], v[154:157], v[136:139], v[82:97]
	s_waitcnt lgkmcnt(0)
; __device__ __forceinline__ int crow(int r, int hi) { return (r & 3) + 8 * (r >> 2) + 4 * hi; }
; template <int MODE, bool SAMPLE>
; __device__ __forceinline__ void attn_unit(const Params& p, char* lds, int b, int h, int qb) {
;     ...
;                 float pmax = p0[0];
; #pragma unroll
;                 for (int r = 1; r < 16; ++r) pmax = fmaxf(pmax, p0[r]);
; #pragma unroll
;                 for (int r = 0; r < 16; ++r) pmax = fmaxf(pmax, p1[r]);
;                 { auto rr = __builtin_amdgcn_permlane32_swap(__float_as_uint(pmax), __float_as_uint(pmax), false, false); pmax = fmaxf(__uint_as_float(rr[0]), __uint_as_float(rr[1])); }
;                 float alpha = 1.f;
;                 if (!__all(pmax - m_reg <= 8.f)) { const float mn = fmaxf(m_reg, pmax); alpha = __builtin_amdgcn_exp2f(m_reg - mn); m_reg = mn; }
;                 float ps = 0.f;
; #pragma unroll
;                 for (int r = 0; r < 16; ++r) { p0[r] = __builtin_amdgcn_exp2f(p0[r] - m_reg); p1[r] = __builtin_amdgcn_exp2f(p1[r] - m_reg); ps += p0[r] + p1[r]; }
;                 { auto rr = __builtin_amdgcn_permlane32_swap(__float_as_uint(ps), __float_as_uint(ps), false, false); ps = __uint_as_float(rr[0]) + __uint_as_float(rr[1]); }
;                 l_reg = l_reg * alpha + ps;
;                 if (__any(alpha < 1.f)) { if (hi == 0) wsc[r32] = alpha; asm volatile("s_waitcnt lgkmcnt(0)" ::: "memory");
; #pragma unroll
;                     for (int d = 0; d < 4; ++d)
; #pragma unroll
;                         for (int r = 0; r < 16; ++r) o[d][r] *= wsc[crow(r, hi)]; }
	v_mfma_f32_32x32x16_bf16 v[66:81], v[170:173], v[136:139], v[66:81]
	s_nop 1
	s_nop 9
	v_max_f32_e32 v163, v83, v83
	v_max_f32_e32 v203, v82, v82
	v_max_f32_e32 v163, v203, v163
	v_max3_f32 v163, v163, v84, v85
	v_max3_f32 v163, v163, v86, v87
	v_max3_f32 v163, v163, v88, v89
	v_max3_f32 v163, v163, v90, v91
	v_max3_f32 v163, v163, v92, v93
	v_max3_f32 v163, v163, v94, v95
	v_max3_f32 v163, v163, v96, v97
	v_max3_f32 v163, v163, v66, v67
	v_max3_f32 v163, v163, v68, v69
	v_max3_f32 v163, v163, v70, v71
	v_max3_f32 v163, v163, v72, v73
	v_max3_f32 v163, v163, v74, v75
	v_max3_f32 v163, v163, v76, v77
	v_max3_f32 v163, v163, v78, v79
	v_max3_f32 v163, v163, v80, v81
	v_mov_b32_e32 v203, v163
	s_nop 1
	v_permlane32_swap_b32_e32 v163, v203
	v_max_f32_e32 v203, v203, v203
	v_max_f32_e32 v163, v163, v163
	v_max_f32_e32 v163, v163, v203
	v_sub_f32_e32 v203, v163, v161
	v_cmp_ge_f32_e32 vcc, s82, v203
	s_cmp_eq_u64 vcc, exec
	v_max_f32_e32 v203, v161, v161
	s_cselect_b64 vcc, -1, 0
	v_max_f32_e32 v163, v203, v163
	v_sub_f32_e32 v203, v161, v163
	v_cndmask_b32_e32 v161, v163, v161, vcc
	v_sub_f32_e32 v82, v82, v161
	v_sub_f32_e32 v66, v66, v161
	v_exp_f32_e32 v163, v82
	v_exp_f32_e32 v82, v66
	v_exp_f32_e32 v204, v203
	v_sub_f32_e32 v67, v67, v161
	v_sub_f32_e32 v68, v68, v161
	v_add_f32_e32 v66, v163, v82
	v_add_f32_e32 v203, 0, v66
	v_sub_f32_e32 v66, v83, v161
	v_exp_f32_e32 v66, v66
	v_exp_f32_e32 v83, v67
	v_sub_f32_e32 v69, v69, v161
	v_sub_f32_e32 v70, v70, v161
	v_exp_f32_e32 v70, v70
	v_add_f32_e32 v67, v66, v83
	v_add_f32_e32 v203, v67, v203
	v_sub_f32_e32 v67, v84, v161
	v_exp_f32_e32 v67, v67
	v_exp_f32_e32 v84, v68
	v_sub_f32_e32 v71, v71, v161
	v_exp_f32_e32 v71, v71
	v_sub_f32_e32 v72, v72, v161
	v_add_f32_e32 v68, v67, v84
	v_add_f32_e32 v203, v68, v203
	v_sub_f32_e32 v68, v85, v161
	v_exp_f32_e32 v68, v68
	v_exp_f32_e32 v85, v69
	v_exp_f32_e32 v72, v72
	v_sub_f32_e32 v73, v73, v161
	v_exp_f32_e32 v73, v73
	v_add_f32_e32 v69, v68, v85
	v_add_f32_e32 v203, v69, v203
	v_sub_f32_e32 v69, v86, v161
	v_exp_f32_e32 v69, v69
	v_sub_f32_e32 v74, v74, v161
	v_exp_f32_e32 v74, v74
	v_sub_f32_e32 v75, v75, v161
	v_add_f32_e32 v86, v69, v70
	v_add_f32_e32 v203, v86, v203
	v_sub_f32_e32 v86, v87, v161
	v_exp_f32_e32 v86, v86
	v_exp_f32_e32 v75, v75
	v_sub_f32_e32 v76, v76, v161
	v_exp_f32_e32 v76, v76
	v_add_f32_e32 v87, v86, v71
	v_add_f32_e32 v203, v87, v203
	v_sub_f32_e32 v87, v88, v161
	v_exp_f32_e32 v87, v87
	v_sub_f32_e32 v77, v77, v161
	v_exp_f32_e32 v77, v77
	v_sub_f32_e32 v78, v78, v161
	v_add_f32_e32 v88, v87, v72
	v_add_f32_e32 v203, v88, v203
	v_sub_f32_e32 v88, v89, v161
	v_exp_f32_e32 v88, v88
	v_exp_f32_e32 v78, v78
	v_sub_f32_e32 v79, v79, v161
	v_exp_f32_e32 v79, v79
	v_add_f32_e32 v89, v88, v73
	v_add_f32_e32 v203, v89, v203
	v_sub_f32_e32 v89, v90, v161
	v_exp_f32_e32 v89, v89
	v_sub_f32_e32 v80, v80, v161
	v_exp_f32_e32 v80, v80
	v_sub_f32_e32 v81, v81, v161
	v_add_f32_e32 v90, v89, v74
	v_add_f32_e32 v203, v90, v203
	v_sub_f32_e32 v90, v91, v161
	v_exp_f32_e32 v90, v90
	v_exp_f32_e32 v81, v81
	v_add_f32_e32 v91, v90, v75
	v_add_f32_e32 v203, v91, v203
	v_sub_f32_e32 v91, v92, v161
	v_exp_f32_e32 v91, v91
	s_nop 0
	v_add_f32_e32 v92, v91, v76
	v_add_f32_e32 v203, v92, v203
	v_sub_f32_e32 v92, v93, v161
	v_exp_f32_e32 v92, v92
	s_nop 0
	v_add_f32_e32 v93, v92, v77
	v_add_f32_e32 v203, v93, v203
	v_sub_f32_e32 v93, v94, v161
	v_exp_f32_e32 v93, v93
	s_nop 0
	v_add_f32_e32 v94, v93, v78
	v_add_f32_e32 v203, v94, v203
	v_sub_f32_e32 v94, v95, v161
	v_exp_f32_e32 v94, v94
	s_nop 0
	v_add_f32_e32 v95, v94, v79
	v_add_f32_e32 v203, v95, v203
	v_sub_f32_e32 v95, v96, v161
	v_exp_f32_e32 v95, v95
	s_nop 0
	v_add_f32_e32 v96, v95, v80
	v_add_f32_e32 v203, v96, v203
	v_sub_f32_e32 v96, v97, v161
	v_exp_f32_e32 v96, v96
	s_nop 0
	v_add_f32_e32 v97, v96, v81
	v_add_f32_e32 v203, v97, v203
	v_cndmask_b32_e64 v97, v204, 1.0, vcc
	v_mov_b32_e32 v204, v203
	s_nop 1
	v_permlane32_swap_b32_e32 v203, v204
	v_cmp_gt_f32_e32 vcc, 1.0, v97
	s_cbranch_vccz .LBB0_850
	s_and_saveexec_b64 s[2:3], s[12:13]
	ds_write_b32 v147, v97
	s_or_b64 exec, exec, s[2:3]
	s_waitcnt lgkmcnt(0)
	ds_read_b128 v[206:209], v149 offset:96
	ds_read_b128 v[212:215], v149 offset:64
	ds_read_b128 v[216:219], v149 offset:32
	ds_read_b128 v[220:223], v149
	s_waitcnt lgkmcnt(3)
	v_pk_mul_f32 v[64:65], v[64:65], v[208:209]
	s_waitcnt lgkmcnt(2)
	v_pk_mul_f32 v[60:61], v[60:61], v[214:215]
	s_waitcnt lgkmcnt(1)
	v_pk_mul_f32 v[56:57], v[56:57], v[218:219]
	s_waitcnt lgkmcnt(0)
	v_pk_mul_f32 v[52:53], v[52:53], v[222:223]
	v_pk_mul_f32 v[62:63], v[62:63], v[206:207]
	v_pk_mul_f32 v[58:59], v[58:59], v[212:213]
	v_pk_mul_f32 v[54:55], v[54:55], v[216:217]
	v_pk_mul_f32 v[50:51], v[50:51], v[220:221]
	v_pk_mul_f32 v[48:49], v[48:49], v[208:209]
	v_pk_mul_f32 v[44:45], v[44:45], v[214:215]
	v_pk_mul_f32 v[40:41], v[40:41], v[218:219]
	v_pk_mul_f32 v[36:37], v[36:37], v[222:223]
	v_pk_mul_f32 v[46:47], v[46:47], v[206:207]
	v_pk_mul_f32 v[42:43], v[42:43], v[212:213]
	v_pk_mul_f32 v[38:39], v[38:39], v[216:217]
	v_pk_mul_f32 v[34:35], v[34:35], v[220:221]
	v_pk_mul_f32 v[32:33], v[32:33], v[208:209]
	v_pk_mul_f32 v[28:29], v[28:29], v[214:215]
	v_pk_mul_f32 v[24:25], v[24:25], v[218:219]
	v_pk_mul_f32 v[20:21], v[20:21], v[222:223]
	v_pk_mul_f32 v[30:31], v[30:31], v[206:207]
	v_pk_mul_f32 v[26:27], v[26:27], v[212:213]
	v_pk_mul_f32 v[22:23], v[22:23], v[216:217]
	v_pk_mul_f32 v[18:19], v[18:19], v[220:221]
	v_pk_mul_f32 v[16:17], v[16:17], v[208:209]
	v_pk_mul_f32 v[12:13], v[12:13], v[214:215]
	v_pk_mul_f32 v[8:9], v[8:9], v[218:219]
	v_pk_mul_f32 v[4:5], v[4:5], v[222:223]
	v_pk_mul_f32 v[14:15], v[14:15], v[206:207]
	v_pk_mul_f32 v[10:11], v[10:11], v[212:213]
	v_pk_mul_f32 v[6:7], v[6:7], v[216:217]
	v_pk_mul_f32 v[2:3], v[2:3], v[220:221]

; __device__ __forceinline__ int crow(int r, int hi) { return (r & 3) + 8 * (r >> 2) + 4 * hi; }
; __device__ __forceinline__ void qkt(f32x16& p0, f32x16& p1, const char* Ks, const char* Qs, int r32, int hi) {
; #pragma unroll
;     for (int d0 = 0; d0 < 8; ++d0) { const int cb = (d0 * 16 + hi * 8) * 2;
;         const bf16x8 qv = *reinterpret_cast<const bf16x8*>(Qs + KSWZ(r32, cb));
;         const bf16x8 b0 = *reinterpret_cast<const bf16x8*>(Ks + KSWZ(r32, cb));
;         const bf16x8 b1 = *reinterpret_cast<const bf16x8*>(Ks + KSWZ(32 + r32, cb));
;         p0 = __builtin_amdgcn_mfma_f32_32x32x16_bf16(b0, qv, p0, 0, 0, 0);
;         p1 = __builtin_amdgcn_mfma_f32_32x32x16_bf16(b1, qv, p1, 0, 0, 0); }
; }
; template <int MODE, bool SAMPLE>
; __device__ __forceinline__ void attn_unit(const Params& p, char* lds, int b, int h, int qb) {
;     ...
;                 const float* bt = biasL + j * 64 + 4 * hi;
; #pragma unroll
;                 for (int g = 0; g < 4; ++g) { const f32x4 a = *(const f32x4*)(bt + 8 * g), c = *(const f32x4*)(bt + 32 + 8 * g);
; #pragma unroll
;                     for (int i = 0; i < 4; ++i) { p0[4 * g + i] = a[i]; p1[4 * g + i] = c[i]; } }
;                 qkt(p0, p1, Kt, Qs, r32, hi);
;                 if (j == jd) {
; #pragma unroll
;                     for (int r = 0; r < 16; ++r) { const int kp = j * 64 + crow(r, hi); if (kp > qpos) p0[r] = -1e30f; if (kp + 32 > qpos) p1[r] = -1e30f; } }
.LBB0_853:
	s_and_b64 vcc, exec, s[0:1]
	v_add_u32_e32 v203, 0, v181
	v_add_u32_e32 v204, 0, v182
	v_add_u32_e32 v205, 0, v184
	v_add_u32_e32 v206, 0, v185
	v_add_u32_e32 v207, 0, v186
	v_add_u32_e32 v208, 0, v187
	v_add_u32_e32 v209, 0, v188
	v_add_u32_e32 v210, 0, v189
	s_waitcnt lgkmcnt(0)
	s_barrier
	s_cbranch_vccnz .LBB0_843
	v_add_u32_e32 v94, s96, v135
	v_add_u32_e32 v66, 0x11000, v94
	v_add_u32_e32 v70, 0x11080, v94
	ds_read_b128 v[66:69], v66
	ds_read_b128 v[82:85], v70
	v_add_u32_e32 v70, 0x11020, v94
	v_add_u32_e32 v74, 0x11040, v94
	v_add_u32_e32 v78, 0x11060, v94
	ds_read_b128 v[70:73], v70
	ds_read_b128 v[74:77], v74
	ds_read_b128 v[78:81], v78
	v_add_u32_e32 v86, 0x110a0, v94
	v_add_u32_e32 v95, 0x110c0, v94
	v_add_u32_e32 v94, 0x110e0, v94
	ds_read_b128 v[86:89], v86
	ds_read_b128 v[90:93], v95
	ds_read_b128 v[94:97], v94
	s_cmp_lg_u32 s96, 0
	v_add_u32_e32 v163, s33, v181
	ds_read_b128 v[216:219], v163
	ds_read_b128 v[212:215], v203
	ds_read_b128 v[174:177], v203 offset:8192
	v_add_u32_e32 v163, s33, v182
	ds_read_b128 v[136:139], v163
	ds_read_b128 v[154:157], v204
	ds_read_b128 v[170:173], v204 offset:8192
	s_waitcnt lgkmcnt(4)
	v_mfma_f32_32x32x16_bf16 v[66:81], v[212:215], v[216:219], v[66:81]
	s_waitcnt lgkmcnt(3)
	v_mfma_f32_32x32x16_bf16 v[82:97], v[174:177], v[216:219], v[82:97]
	v_add_u32_e32 v163, s33, v184
	ds_read_b128 v[216:219], v163
	ds_read_b128 v[212:215], v205
	ds_read_b128 v[174:177], v205 offset:8192
	s_waitcnt lgkmcnt(4)
	v_mfma_f32_32x32x16_bf16 v[66:81], v[154:157], v[136:139], v[66:81]
	s_waitcnt lgkmcnt(3)
	v_mfma_f32_32x32x16_bf16 v[82:97], v[170:173], v[136:139], v[82:97]
	v_add_u32_e32 v163, s33, v185
	ds_read_b128 v[136:139], v163
	ds_read_b128 v[154:157], v206
	ds_read_b128 v[170:173], v206 offset:8192
	s_waitcnt lgkmcnt(4)
	v_mfma_f32_32x32x16_bf16 v[66:81], v[212:215], v[216:219], v[66:81]
	s_waitcnt lgkmcnt(3)
	v_mfma_f32_32x32x16_bf16 v[82:97], v[174:177], v[216:219], v[82:97]
	v_add_u32_e32 v163, s33, v186
	ds_read_b128 v[216:219], v163
	ds_read_b128 v[212:215], v207
	ds_read_b128 v[174:177], v207 offset:8192
	s_waitcnt lgkmcnt(4)
	v_mfma_f32_32x32x16_bf16 v[66:81], v[154:157], v[136:139], v[66:81]
	s_waitcnt lgkmcnt(3)
	v_mfma_f32_32x32x16_bf16 v[82:97], v[170:173], v[136:139], v[82:97]
	v_add_u32_e32 v163, s33, v187
	ds_read_b128 v[136:139], v163
	ds_read_b128 v[154:157], v208
	ds_read_b128 v[170:173], v208 offset:8192
	s_waitcnt lgkmcnt(4)
	v_mfma_f32_32x32x16_bf16 v[66:81], v[212:215], v[216:219], v[66:81]
	s_waitcnt lgkmcnt(3)
	v_mfma_f32_32x32x16_bf16 v[82:97], v[174:177], v[216:219], v[82:97]
	v_add_u32_e32 v163, s33, v188
	ds_read_b128 v[216:219], v163
	ds_read_b128 v[212:215], v209
	ds_read_b128 v[174:177], v209 offset:8192
	s_waitcnt lgkmcnt(4)
	v_mfma_f32_32x32x16_bf16 v[66:81], v[154:157], v[136:139], v[66:81]
	s_waitcnt lgkmcnt(3)
	v_mfma_f32_32x32x16_bf16 v[82:97], v[170:173], v[136:139], v[82:97]
	v_add_u32_e32 v163, s33, v189
	ds_read_b128 v[136:139], v163
	ds_read_b128 v[154:157], v210
	ds_read_b128 v[170:173], v210 offset:8192
	s_waitcnt lgkmcnt(4)
	v_mfma_f32_32x32x16_bf16 v[66:81], v[212:215], v[216:219], v[66:81]
	s_waitcnt lgkmcnt(3)
	v_mfma_f32_32x32x16_bf16 v[82:97], v[174:177], v[216:219], v[82:97]
	s_waitcnt lgkmcnt(1)
	v_mfma_f32_32x32x16_bf16 v[66:81], v[154:157], v[136:139], v[66:81]
	s_waitcnt lgkmcnt(0)
	v_mfma_f32_32x32x16_bf16 v[82:97], v[170:173], v[136:139], v[82:97]
	s_nop 1
	s_cbranch_scc1 .LBB0_856
	s_nop 10
	v_mov_b32_e32 v82, 0xf149f2ca
	v_cndmask_b32_e64 v74, v66, v82, s[20:21]
	v_cndmask_b32_e64 v66, v74, v66, s[22:23]
	v_cndmask_b32_e64 v67, v82, v67, s[22:23]
	v_cndmask_b32_e64 v68, v68, v82, s[24:25]
	v_cndmask_b32_e64 v69, v69, v82, s[26:27]
	v_cndmask_b32_e64 v70, v70, v82, s[28:29]
	v_cndmask_b32_e64 v71, v71, v82, s[30:31]
	v_cndmask_b32_e64 v72, v72, v82, s[34:35]
	v_cndmask_b32_e64 v73, v73, v82, s[18:19]
	v_mov_b32_e32 v83, v82
	v_mov_b32_e32 v84, v82
	v_mov_b32_e32 v85, v82
	v_mov_b32_e32 v86, v82
	v_mov_b32_e32 v87, v82
	v_mov_b32_e32 v88, v82
	v_mov_b32_e32 v89, v82
	v_mov_b32_e32 v90, v82
	v_mov_b32_e32 v91, v82
	v_mov_b32_e32 v92, v82
	v_mov_b32_e32 v93, v82
	v_mov_b32_e32 v94, v82
	v_mov_b32_e32 v95, v82
	v_mov_b32_e32 v96, v82
	v_mov_b32_e32 v97, v82
	v_mov_b32_e32 v74, v82
	v_mov_b32_e32 v75, v82
	v_mov_b32_e32 v76, v82
	v_mov_b32_e32 v77, v82
	v_mov_b32_e32 v78, v82
	v_mov_b32_e32 v79, v82
	v_mov_b32_e32 v80, v82
	v_mov_b32_e32 v81, v82

; template <int MODE, bool SAMPLE>
; __device__ __forceinline__ void attn_unit(const Params& p, char* lds, int b, int h, int qb) {
;     ...
;     if (wact && var < 1) {
;         bf16_t* MIX = (bf16_t*)(p.ws + (var == 0 ? WS_MIX : WS_ACT));
;         const size_t rbase = SAMPLE ? (size_t)(MP + b * TS) : (size_t)(b * SEQ + qb * 256 + wid * 32);
;         constexpr int NIT = SAMPLE ? 4 : 8; const int er = lane >> 4, ec = (lane & 15) * 8;
.LBB0_859:
	s_waitcnt vmcnt(0)
	v_mov_b32_e32 v141, v250
	v_mov_b32_e32 v143, v251
	v_mov_b32_e32 v130, v252
	v_lshlrev_b32_e32 v250, 4, v183
	v_add_u32_e32 v250, 0x15000, v250
	ds_read_b128 v[136:139], v250
	ds_read_b128 v[154:157], v250 offset:8192
	ds_read_b128 v[170:173], v250 offset:16384
	ds_read_b128 v[174:177], v250 offset:24576
	s_waitcnt lgkmcnt(0)
	v_and_b32_e32 v131, 31, v183
	v_bfe_u32 v132, v183, 4, 2
	v_lshlrev_b32_e32 v133, 8, v131
	v_or_b32_e32 v140, 8, v132
	v_or_b32_e32 v142, 12, v132
	v_lshlrev_b32_e32 v192, 1, v131
	v_lshlrev_b32_e32 v193, 8, v132
	v_lshlrev_b32_e32 v194, 8, v138
	v_lshlrev_b32_e32 v195, 8, v140
	s_andn2_b64 vcc, exec, s[72:73]
	s_mov_b64 s[0:1], -1
	s_cbranch_vccnz .LBB0_861
	s_mov_b32 s61, s53
	s_mov_b64 s[0:1], 0
